# gla_a: U^T dwordx2 store pairs merged into dwordx4 via v_permlane16_swap (64B contiguous per row)
# speedup vs baseline: 1.0563x; 1.0058x over previous
.LBB0_663:
	s_or_b64 exec, exec, s[0:1]
	v_add_u32_e32 v2, s43, v144
	v_mov_b64_e32 v[0:1], s[20:21]
	v_mad_i64_i32 v[0:1], s[0:1], v2, s37, v[0:1]
	s_lshl_b32 s22, s22, 1
	v_lshl_add_u64 v[0:1], v[0:1], 0, s[22:23]
	v_mov_b32_e32 v41, v31
	v_lshl_add_u64 v[0:1], v[0:1], 0, v[40:41]
	global_load_dwordx4 v[8:11], v[0:1], off offset:2368
	global_load_dwordx4 v[12:15], v[0:1], off offset:3392
	v_add_u32_e32 v2, 0x8100, v77
	v_add_u32_e32 v3, 0x8108, v77
	v_add_u32_e32 v4, 0x8110, v77
	v_add_u32_e32 v5, 0x8200, v77
	ds_read_b128 v[16:19], v76
	ds_read2_b32 v[28:29], v77 offset1:1
	ds_read_b128 v[20:23], v78
	ds_read_b96 v[24:26], v87
	ds_read_b96 v[42:44], v88
	ds_read2_b32 v[46:47], v77 offset0:2 offset1:3
	ds_read2_b32 v[48:49], v77 offset0:4 offset1:5
	ds_read2_b32 v[50:51], v77 offset0:64 offset1:65
	ds_read2_b32 v[52:53], v77 offset0:66 offset1:67
	ds_read2_b32 v[54:55], v2 offset1:1
	ds_read2_b32 v[56:57], v3 offset1:1
	ds_read2_b32 v[58:59], v4 offset1:1
	ds_read2_b32 v[60:61], v5 offset1:1
	global_load_dwordx4 v[4:7], v[0:1], off offset:2496
	s_nop 0
	global_load_dwordx4 v[0:3], v[0:1], off offset:3520
	s_waitcnt lgkmcnt(7)
	v_sub_f32_e32 v19, v19, v47
	v_sub_f32_e32 v16, v16, v28
	v_sub_f32_e32 v17, v17, v29
	s_waitcnt lgkmcnt(3)
	v_sub_f32_e32 v21, v21, v55
	s_waitcnt lgkmcnt(2)
	v_sub_f32_e32 v23, v23, v57
	v_sub_f32_e32 v18, v18, v46
	v_mul_f32_e32 v16, 0x3fb8aa3b, v16
	v_sub_f32_e32 v20, v20, v54
	v_mul_f32_e32 v17, 0x3fb8aa3b, v17
	v_sub_f32_e32 v22, v22, v56
	v_mul_f32_e32 v19, 0x3fb8aa3b, v19
	v_mul_f32_e32 v21, 0x3fb8aa3b, v21
	v_mul_f32_e32 v23, 0x3fb8aa3b, v23
	v_mul_f32_e32 v18, 0x3fb8aa3b, v18
	v_exp_f32_e32 v16, v16
	v_mul_f32_e32 v20, 0x3fb8aa3b, v20
	v_exp_f32_e32 v17, v17
	v_mul_f32_e32 v22, 0x3fb8aa3b, v22
	v_exp_f32_e32 v19, v19
	v_exp_f32_e32 v21, v21
	v_exp_f32_e32 v23, v23
	v_exp_f32_e32 v18, v18
	v_exp_f32_e32 v20, v20
	v_exp_f32_e32 v22, v22
	v_sub_f32_e32 v24, v24, v48
	v_mul_f32_e32 v24, 0x3fb8aa3b, v24
	s_mov_b32 s29, s23
	s_waitcnt vmcnt(3)
	v_lshlrev_b32_e32 v27, 16, v8
	v_and_b32_e32 v8, 0xffff0000, v8
	v_lshlrev_b32_e32 v28, 16, v9
	v_and_b32_e32 v9, 0xffff0000, v9
	v_mul_f32_e32 v16, v16, v27
	v_mul_f32_e32 v17, v17, v8
	v_mul_f32_e32 v8, v21, v8
	v_mul_f32_e32 v19, v19, v9
	v_mul_f32_e32 v9, v23, v9
	v_mul_f32_e32 v20, v20, v27
	v_mul_f32_e32 v18, v18, v28
	v_mul_f32_e32 v21, v22, v28
	v_cvt_pk_bf16_f32 v16, v16, s0
	v_cvt_pk_bf16_f32 v8, v8, s0
	v_cvt_pk_bf16_f32 v9, v9, s0
	v_cvt_pk_bf16_f32 v20, v20, s0
	v_cvt_pk_bf16_f32 v17, v17, s0
	v_cvt_pk_bf16_f32 v18, v18, s0
	v_cvt_pk_bf16_f32 v21, v21, s0
	v_cvt_pk_bf16_f32 v19, v19, s0
	ds_write_b16 v79, v16
	ds_write_b16 v121, v20
	s_waitcnt vmcnt(2)
	ds_write_b16 v80, v12
	ds_write_b16 v81, v17
	ds_write_b16 v121, v8 offset:144
	ds_write_b16_d16_hi v82, v12
	ds_write_b16 v83, v18
	ds_write_b16 v121, v21 offset:288
	ds_write_b16 v84, v13
	ds_write_b16 v85, v19
	ds_write_b16 v121, v9 offset:432
	ds_write_b16_d16_hi v86, v13
	v_exp_f32_e32 v8, v24
	s_waitcnt lgkmcnt(13)
	v_sub_f32_e32 v9, v42, v58
	v_mul_f32_e32 v9, 0x3fb8aa3b, v9
	v_exp_f32_e32 v9, v9
	v_lshlrev_b32_e32 v29, 16, v10
	v_mul_f32_e32 v8, v8, v29
	v_cvt_pk_bf16_f32 v8, v8, s0
	ds_read_b32 v12, v95
	ds_read_b32 v13, v97
	ds_write_b16 v89, v8
	v_mul_f32_e32 v8, v9, v29
	v_cvt_pk_bf16_f32 v8, v8, s0
	v_sub_f32_e32 v9, v25, v49
	ds_write_b16 v121, v8 offset:576
	ds_write_b16 v90, v14
	v_and_b32_e32 v8, 0xffff0000, v10
	v_mul_f32_e32 v9, 0x3fb8aa3b, v9
	v_sub_f32_e32 v10, v43, v59
	v_exp_f32_e32 v9, v9
	v_mul_f32_e32 v10, 0x3fb8aa3b, v10
	v_exp_f32_e32 v10, v10
	s_waitcnt vmcnt(1)
	v_lshlrev_b32_e32 v16, 16, v4
	v_mul_f32_e32 v9, v9, v8
	v_cvt_pk_bf16_f32 v9, v9, s0
	v_mul_f32_e32 v10, v10, v8
	v_add_u32_e32 v8, 24, v77
	ds_write_b16 v91, v9
	ds_read2st64_b32 v[8:9], v8 offset1:129
	v_cvt_pk_bf16_f32 v10, v10, s0
	ds_write_b16 v121, v10 offset:720
	ds_write_b16_d16_hi v92, v14
	v_lshlrev_b32_e32 v10, 16, v11
	v_and_b32_e32 v4, 0xffff0000, v4
	s_waitcnt lgkmcnt(2)
	v_sub_f32_e32 v8, v26, v8
	v_mul_f32_e32 v8, 0x3fb8aa3b, v8
	v_exp_f32_e32 v8, v8
	v_sub_f32_e32 v9, v44, v9
	v_mul_f32_e32 v9, 0x3fb8aa3b, v9
	v_exp_f32_e32 v9, v9
	v_mul_f32_e32 v8, v8, v10
	v_cvt_pk_bf16_f32 v8, v8, s0
	ds_write_b16 v93, v8
	v_mul_f32_e32 v10, v9, v10
	ds_read2st64_b32 v[8:9], v96 offset1:129
	v_cvt_pk_bf16_f32 v10, v10, s0
	ds_write_b16 v121, v10 offset:864
	ds_write_b16 v94, v15
	v_and_b32_e32 v10, 0xffff0000, v11
	v_lshlrev_b32_e32 v20, 16, v6
	s_waitcnt lgkmcnt(2)
	v_sub_f32_e32 v8, v12, v8
	v_mul_f32_e32 v8, 0x3fb8aa3b, v8
	v_exp_f32_e32 v8, v8
	v_sub_f32_e32 v9, v13, v9
	v_mul_f32_e32 v9, 0x3fb8aa3b, v9
	v_exp_f32_e32 v9, v9
	v_mul_f32_e32 v8, v8, v10
	v_cvt_pk_bf16_f32 v8, v8, s0
	ds_write_b16 v98, v8
	v_mul_f32_e32 v8, v9, v10
	v_cvt_pk_bf16_f32 v12, v8, s0
	ds_read_b128 v[8:11], v100
	ds_write_b16 v122, v12
	ds_write_b16_d16_hi v99, v15
	ds_read_b128 v[12:15], v101
	s_waitcnt lgkmcnt(3)
	v_sub_f32_e32 v8, v8, v50
	v_mul_f32_e32 v8, 0x3fb8aa3b, v8
	v_exp_f32_e32 v8, v8
	s_waitcnt lgkmcnt(0)
	v_sub_f32_e32 v12, v12, v60
	v_mul_f32_e32 v12, 0x3fb8aa3b, v12
	v_exp_f32_e32 v12, v12
	v_mul_f32_e32 v8, v8, v16
	v_cvt_pk_bf16_f32 v8, v8, s0
	ds_write_b16 v102, v8
	v_mul_f32_e32 v8, v12, v16
	v_cvt_pk_bf16_f32 v8, v8, s0
	ds_write_b16 v121, v8 offset:9216
	s_waitcnt vmcnt(0)
	ds_write_b16 v103, v0
	v_sub_f32_e32 v8, v9, v51
	v_sub_f32_e32 v9, v13, v61
	v_mul_f32_e32 v8, 0x3fb8aa3b, v8
	v_mul_f32_e32 v9, 0x3fb8aa3b, v9
	v_exp_f32_e32 v8, v8
	v_exp_f32_e32 v9, v9
	v_add_u32_e32 v12, 0x8218, v77
	v_mul_f32_e32 v8, v8, v4
	v_mul_f32_e32 v4, v9, v4
	v_cvt_pk_bf16_f32 v8, v8, s0
	v_cvt_pk_bf16_f32 v4, v4, s0
	ds_write_b16 v104, v8
	ds_write_b16 v121, v4 offset:9360
	ds_write_b16_d16_hi v105, v0
	v_add_u32_e32 v8, 0x8208, v77
	ds_read2_b32 v[8:9], v8 offset1:1
	v_sub_f32_e32 v4, v10, v52
	v_mul_f32_e32 v4, 0x3fb8aa3b, v4
	v_exp_f32_e32 v4, v4
	v_lshlrev_b32_e32 v0, 16, v5
	s_waitcnt lgkmcnt(0)
	v_sub_f32_e32 v8, v14, v8
	v_mul_f32_e32 v8, 0x3fb8aa3b, v8
	v_exp_f32_e32 v8, v8
	v_mul_f32_e32 v4, v4, v0
	v_add_u32_e32 v10, 0x8210, v77
	v_cvt_pk_bf16_f32 v4, v4, s0
	v_mul_f32_e32 v0, v8, v0
	v_cvt_pk_bf16_f32 v0, v0, s0
	ds_read2_b32 v[16:17], v10 offset1:1
	ds_read2_b32 v[18:19], v12 offset1:1
	ds_write_b16 v106, v4
	ds_write_b16 v121, v0 offset:9504
	ds_write_b16 v107, v1
	v_and_b32_e32 v0, 0xffff0000, v5
	v_sub_f32_e32 v4, v11, v53
	v_sub_f32_e32 v5, v15, v9
	v_mul_f32_e32 v4, 0x3fb8aa3b, v4
	v_mul_f32_e32 v5, 0x3fb8aa3b, v5
	v_exp_f32_e32 v4, v4
	v_exp_f32_e32 v5, v5
	v_mul_f32_e32 v4, v4, v0
	v_mul_f32_e32 v0, v5, v0
	v_cvt_pk_bf16_f32 v4, v4, s0
	v_cvt_pk_bf16_f32 v0, v0, s0
	ds_write_b16 v108, v4
	ds_write_b16 v121, v0 offset:9648
	ds_read_b128 v[8:11], v110
	ds_read2_b32 v[4:5], v77 offset0:68 offset1:69
	ds_write_b16_d16_hi v109, v1
	ds_read_b128 v[12:15], v111
	ds_read2_b32 v[0:1], v77 offset0:70 offset1:71
	s_waitcnt lgkmcnt(3)
	v_sub_f32_e32 v4, v8, v4
	v_mul_f32_e32 v4, 0x3fb8aa3b, v4
	v_exp_f32_e32 v4, v4
	s_waitcnt lgkmcnt(1)
	v_sub_f32_e32 v8, v12, v16
	v_mul_f32_e32 v8, 0x3fb8aa3b, v8
	v_exp_f32_e32 v8, v8
	v_mul_f32_e32 v4, v4, v20
	v_cvt_pk_bf16_f32 v4, v4, s0
	ds_write_b16 v112, v4
	v_mul_f32_e32 v4, v8, v20
	v_cvt_pk_bf16_f32 v4, v4, s0
	ds_write_b16 v121, v4 offset:9792
	ds_write_b16 v113, v2
	v_and_b32_e32 v4, 0xffff0000, v6
	v_sub_f32_e32 v5, v9, v5
	v_sub_f32_e32 v6, v13, v17
	v_mul_f32_e32 v5, 0x3fb8aa3b, v5
	v_mul_f32_e32 v6, 0x3fb8aa3b, v6
	v_exp_f32_e32 v5, v5
	v_exp_f32_e32 v6, v6
	s_waitcnt lgkmcnt(3)
	v_sub_f32_e32 v0, v10, v0
	v_mul_f32_e32 v0, 0x3fb8aa3b, v0
	v_mul_f32_e32 v5, v5, v4
	v_mul_f32_e32 v4, v6, v4
	v_cvt_pk_bf16_f32 v5, v5, s0
	v_cvt_pk_bf16_f32 v4, v4, s0
	ds_write_b16 v114, v5
	ds_write_b16 v121, v4 offset:9936
	ds_write_b16_d16_hi v115, v2
	v_exp_f32_e32 v0, v0
	v_sub_f32_e32 v4, v14, v18
	v_mul_f32_e32 v4, 0x3fb8aa3b, v4
	v_exp_f32_e32 v4, v4
	v_lshlrev_b32_e32 v2, 16, v7
	v_mul_f32_e32 v0, v0, v2
	v_cvt_pk_bf16_f32 v0, v0, s0
	ds_write_b16 v116, v0
	v_mul_f32_e32 v0, v4, v2
	v_sub_f32_e32 v1, v11, v1
	v_sub_f32_e32 v2, v15, v19
	v_mul_f32_e32 v1, 0x3fb8aa3b, v1
	v_mul_f32_e32 v2, 0x3fb8aa3b, v2
	v_exp_f32_e32 v1, v1
	v_exp_f32_e32 v2, v2
	v_cvt_pk_bf16_f32 v0, v0, s0
	ds_write_b16 v121, v0 offset:10080
	ds_write_b16 v117, v3
	v_and_b32_e32 v0, 0xffff0000, v7
	v_mul_f32_e32 v1, v1, v0
	v_mul_f32_e32 v0, v2, v0
	v_cvt_pk_bf16_f32 v1, v1, s0
	v_cvt_pk_bf16_f32 v0, v0, s0
	s_add_i32 s0, s12, s31
	ds_write_b16 v118, v1
	ds_write_b16 v121, v0 offset:10224
	ds_write_b16_d16_hi v119, v3
	s_waitcnt lgkmcnt(0)
	s_barrier
	ds_read_b128 v[0:3], v123
	ds_read_b128 v[4:7], v123 offset:64
	ds_read_b128 v[8:11], v124
	ds_read_b128 v[12:15], v124 offset:64
	s_ashr_i32 s1, s0, 31
	s_and_b64 s[12:13], exec, s[26:27]
	s_cselect_b32 s13, s36, s53
	s_cselect_b32 s12, s35, s52
	s_cselect_b32 s14, 17, 21
	s_lshl_b64 s[0:1], s[0:1], s14
	v_lshl_add_u64 v[16:17], s[12:13], 0, v[38:39]
	s_lshl_b64 s[12:13], s[28:29], 15
	s_add_u32 s0, s0, s12
	s_addc_u32 s1, s1, s13
	v_lshl_add_u64 v[16:17], v[16:17], 0, s[0:1]
	v_bfe_u32 v148, v144, 4, 1
	v_mul_u32_u24_e32 v148, 24, v148
	v_mov_b32_e32 v149, 0
	v_lshl_add_u64 v[16:17], v[16:17], 0, v[148:149]
	s_mov_b32 s0, 0
.LBB0_664:
	v_add_u32_e32 v41, s0, v120
	v_add_u32_e32 v18, 0x1b800, v41
	v_add_u32_e32 v22, 0x1b840, v41
	ds_read_b128 v[18:21], v18
	ds_read_b128 v[22:25], v22
	v_add_u32_e32 v42, 0x1c100, v41
	v_add_u32_e32 v41, 0x1c140, v41
	ds_read_b128 v[42:45], v42
	ds_read_b128 v[46:49], v41
	s_waitcnt lgkmcnt(3)
	v_mfma_f32_16x16x32_bf16 v[26:29], v[0:3], v[18:21], 0
	s_addk_i32 s0, 0x1200
	s_cmpk_lg_i32 s0, 0x4800
	v_mfma_f32_16x16x32_bf16 v[18:21], v[8:11], v[18:21], 0
	s_waitcnt lgkmcnt(1)
	v_mfma_f32_16x16x32_bf16 v[50:53], v[0:3], v[42:45], 0
	v_mfma_f32_16x16x32_bf16 v[42:45], v[8:11], v[42:45], 0
	v_mfma_f32_16x16x32_bf16 v[26:29], v[4:7], v[22:25], v[26:29]
	v_mfma_f32_16x16x32_bf16 v[18:21], v[12:15], v[22:25], v[18:21]
	s_waitcnt lgkmcnt(0)
	v_mfma_f32_16x16x32_bf16 v[22:25], v[4:7], v[46:49], v[50:53]
	s_nop 4
	v_cvt_pk_bf16_f32 v26, v26, v27
	v_cvt_pk_bf16_f32 v27, v28, v29
	v_cvt_pk_bf16_f32 v28, v18, v19
	v_mfma_f32_16x16x32_bf16 v[42:45], v[12:15], v[46:49], v[42:45]
	v_cvt_pk_bf16_f32 v29, v20, v21
	v_cvt_pk_bf16_f32 v20, v22, v23
	v_cvt_pk_bf16_f32 v21, v24, v25
	s_nop 4
	v_cvt_pk_bf16_f32 v22, v42, v43
	v_cvt_pk_bf16_f32 v23, v44, v45
	v_permlane16_swap_b32_e32 v26, v28
	v_permlane16_swap_b32_e32 v27, v29
	s_nop 0
	v_permlane16_swap_b32_e32 v20, v22
	v_permlane16_swap_b32_e32 v21, v23
	global_store_dwordx4 v[16:17], v[26:29], off offset:-4096
	global_store_dwordx4 v[16:17], v[20:23], off
	v_lshl_add_u64 v[16:17], v[16:17], 0, s[24:25]
	s_cbranch_scc1 .LBB0_664
	s_add_i32 s30, s30, s72
	s_cmpk_lt_i32 s30, 0x880
	s_barrier
	s_cbranch_scc1 .LBB0_647
